# P4-head and P6-head deferred layer-1 transposes both on even-numbered workgroups
# baseline (speedup 1.0000x reference)
.LBB0_627:
	s_or_b64 exec, exec, s[0:1]
	s_bitcmp1_b32 s2, 0
	s_cbranch_scc1 .Ldf_skip_p4
	v_writelane_b32 v234, s0, 0
	v_writelane_b32 v234, s1, 1
	v_writelane_b32 v234, s2, 2
	v_writelane_b32 v234, s3, 3
	v_writelane_b32 v234, s4, 4
	v_writelane_b32 v234, s5, 5
	v_writelane_b32 v234, s6, 6
	v_writelane_b32 v234, s7, 7
	v_writelane_b32 v234, s8, 8
	v_writelane_b32 v234, s9, 9
	v_writelane_b32 v234, s10, 10
	v_writelane_b32 v234, s11, 11
	v_writelane_b32 v234, s12, 12
	v_writelane_b32 v234, s13, 13
	v_writelane_b32 v234, s14, 14
	v_writelane_b32 v234, s15, 15
	v_writelane_b32 v234, s16, 16
	v_writelane_b32 v234, s17, 17
	v_writelane_b32 v234, s18, 18
	v_writelane_b32 v234, s19, 19
	v_writelane_b32 v234, s20, 20
	v_writelane_b32 v234, s21, 21
	v_writelane_b32 v234, s22, 22
	v_writelane_b32 v234, s23, 23
	v_writelane_b32 v234, s24, 24
	v_writelane_b32 v234, s25, 25
	v_writelane_b32 v234, s26, 26
	v_writelane_b32 v234, s27, 27
	v_writelane_b32 v234, s28, 28
	v_writelane_b32 v234, s29, 29
	v_writelane_b32 v234, s30, 30
	v_writelane_b32 v234, s31, 31
	v_writelane_b32 v234, s32, 32
	v_writelane_b32 v234, s33, 33
	v_writelane_b32 v234, s34, 34
	v_writelane_b32 v234, s35, 35
	v_writelane_b32 v234, s36, 36
	v_writelane_b32 v234, s37, 37
	v_writelane_b32 v234, s38, 38
	v_writelane_b32 v234, s39, 39
	v_writelane_b32 v234, s40, 40
	v_writelane_b32 v234, s41, 41
	v_writelane_b32 v234, s42, 42
	v_writelane_b32 v234, s43, 43
	v_writelane_b32 v234, s44, 44
	v_writelane_b32 v234, s45, 45
	v_writelane_b32 v234, s46, 46
	v_writelane_b32 v234, s47, 47
	v_writelane_b32 v234, s48, 48
	v_writelane_b32 v234, s49, 49
	v_writelane_b32 v234, s50, 50
	v_writelane_b32 v234, s51, 51
	v_writelane_b32 v234, s52, 52
	v_writelane_b32 v234, s53, 53
	v_writelane_b32 v234, s54, 54
	v_writelane_b32 v234, s55, 55
	v_writelane_b32 v234, s56, 56
	v_writelane_b32 v234, s57, 57
	v_writelane_b32 v234, s58, 58
	v_writelane_b32 v234, s59, 59
	v_writelane_b32 v234, s60, 60
	v_writelane_b32 v234, s61, 61
	v_writelane_b32 v234, s62, 62
	v_writelane_b32 v234, s63, 63
	v_writelane_b32 v235, s64, 0
	v_writelane_b32 v235, s65, 1
	v_writelane_b32 v235, s66, 2
	v_writelane_b32 v235, s67, 3
	v_writelane_b32 v235, s68, 4
	v_writelane_b32 v235, s69, 5
	v_writelane_b32 v235, s70, 6
	v_writelane_b32 v235, s71, 7
	v_writelane_b32 v235, s72, 8
	v_writelane_b32 v235, s73, 9
	v_writelane_b32 v235, s74, 10
	v_writelane_b32 v235, s75, 11
	v_writelane_b32 v235, s76, 12
	v_writelane_b32 v235, s77, 13
	v_writelane_b32 v235, s78, 14
	v_writelane_b32 v235, s79, 15
	v_writelane_b32 v235, s80, 16
	v_writelane_b32 v235, s81, 17
	v_writelane_b32 v235, s82, 18
	v_writelane_b32 v235, s83, 19
	v_writelane_b32 v235, s84, 20
	v_writelane_b32 v235, s85, 21
	v_writelane_b32 v235, s86, 22
	v_writelane_b32 v235, s87, 23
	v_writelane_b32 v235, s88, 24
	v_writelane_b32 v235, s89, 25
	v_writelane_b32 v235, s90, 26
	v_writelane_b32 v235, s91, 27
	v_writelane_b32 v235, s92, 28
	v_writelane_b32 v235, s93, 29
	v_writelane_b32 v235, s94, 30
	v_writelane_b32 v235, s95, 31
	v_writelane_b32 v235, s96, 32
	v_writelane_b32 v235, s97, 33
	v_writelane_b32 v235, vcc_lo, 34
	v_writelane_b32 v235, vcc_hi, 35
	v_readlane_b32 s70, v233, 45
	v_readlane_b32 s71, v233, 46
	s_add_u32 s22, s92, 0x4500000
	s_addc_u32 s23, s93, 0
	s_add_u32 s40, s92, 0x1400000
	s_addc_u32 s41, s93, 0
	v_mov_b32_e32 v0, v210
	s_nop 0
	v_readfirstlane_b32 s1, v0
	s_nop 3
	s_ashr_i32 s13, s1, 6
	s_lshr_b32 s0, s2, 1
	s_lshl_b32 s0, s0, 3
	s_add_i32 s33, s13, s0
	s_addk_i32 s33, 0x1000
	s_movk_i32 s12, 0x80
	s_movk_i32 s101, 0x1c00
	s_mov_b32 s100, 4
	s_branch .Lp3t_setup
